# P2b->P4 split-phase barrier: wait deferred into the first P4 GEMM (its inputs predate P2b), XCD-leader writeback at arrival
# speedup vs baseline: 1.0290x; 1.0110x over previous
.LBB0_615:
	s_waitcnt vmcnt(0)
	s_waitcnt vmcnt(0) lgkmcnt(0)
	s_barrier
	s_and_saveexec_b64 s[10:11], s[92:93]
	s_cbranch_execz .LBB0_676
	v_mov_b32_e32 v2, 0x22000
	ds_read_b32 v4, v2
	s_lshl_b32 s0, s87, 8
	s_add_i32 s0, s0, 0x2b5d020
	v_mov_b32_e32 v2, s0
	v_mov_b32_e32 v3, 1
	global_atomic_add v6, v2, v3, s[88:89] sc0
	s_waitcnt vmcnt(0) lgkmcnt(0)
	v_add_u32_e32 v6, 1, v6
	v_cmp_eq_u32_e32 vcc, v6, v4
	s_cbranch_vccz .LBB0_676
	buffer_wbl2 sc1
	s_waitcnt vmcnt(0)
	v_mov_b32_e32 v2, 0x2b5d024
	global_atomic_add v2, v3, s[88:89]
	s_branch .LBB0_676
	s_add_i32 s0, 0, 0x22000
	v_mov_b32_e32 v2, s0
	s_waitcnt vmcnt(0) expcnt(0) lgkmcnt(0)
	ds_read_b32 v4, v2
	s_add_i32 s0, 0, 0x22004
	v_mov_b32_e32 v2, s0
	ds_read_b32 v2, v2
	s_waitcnt lgkmcnt(1)
	v_cmp_ne_u32_e32 vcc, 0, v4
	s_cbranch_vccnz .LBB0_631
	s_add_u32 s12, s88, 0x2b59200
	s_addc_u32 s13, s89, 0
	s_add_u32 s14, s88, 0x2b59400
	s_addc_u32 s15, s89, 0
	s_add_u32 s16, s88, 0x2b59500
	s_addc_u32 s17, s89, 0
	s_add_u32 s18, s88, 0x2b59600
	s_addc_u32 s19, s89, 0
	s_add_u32 s20, s88, 0x2b59700
	s_addc_u32 s21, s89, 0
	s_add_u32 s22, s88, 0x2b59800
	s_addc_u32 s23, s89, 0
	s_add_u32 s42, s88, 0x2b59900
	s_addc_u32 s43, s89, 0
	s_add_u32 s44, s88, 0x2b59a00
	s_addc_u32 s45, s89, 0
	s_add_u32 s46, s88, 0x2b59b00
	s_addc_u32 s47, s89, 0
	s_add_u32 s48, s88, 0x2b59c00
	s_addc_u32 s49, s89, 0
	s_add_u32 s50, s88, 0x2b59d00
	s_addc_u32 s51, s89, 0
	s_add_u32 s52, s88, 0x2b59e00
	s_addc_u32 s53, s89, 0
	s_add_u32 s54, s88, 0x2b59f00
	s_addc_u32 s55, s89, 0
	s_add_u32 s56, s88, 0x2b5a000
	s_addc_u32 s57, s89, 0
	s_add_u32 s58, s88, 0x2b5a100
	s_addc_u32 s59, s89, 0
	s_add_u32 s60, s88, 0x2b5a200
	v_readlane_b32 s0, v254, 0
	s_addc_u32 s61, s89, 0
	s_mul_i32 s0, s91, s0
	s_add_u32 s62, s88, 0x2b5a300
	s_mul_i32 s0, s0, s90
	s_addc_u32 s63, s89, 0
	s_mov_b32 s1, 1
	v_mov_b32_e32 v18, 0
	s_branch .LBB0_619

.LBB0_687:
	ds_read_b128 v[4:7], v158
	ds_read_b128 v[8:11], v158 offset:1024
	ds_read_b128 v[12:15], v158 offset:2048
	ds_read_b128 v[16:19], v158 offset:3072
	v_lshl_add_u64 v[2:3], s[80:81], 0, v[140:141]
	s_mov_b64 s[0:1], 0x10080
	s_add_i32 s77, s28, 0xc000
	v_lshl_add_u64 v[52:53], v[2:3], 0, s[0:1]
	s_mov_b32 m0, s77
	s_mov_b64 s[0:1], 0x18080
	ds_read_b128 v[20:23], v159
	ds_read_b128 v[24:27], v159 offset:1024
	ds_read_b128 v[28:31], v159 offset:2048
	ds_read_b128 v[32:35], v159 offset:3072
	ds_read_b128 v[36:39], v159 offset:4096
	ds_read_b128 v[40:43], v159 offset:5120
	ds_read_b128 v[44:47], v159 offset:6144
	ds_read_b128 v[48:51], v159 offset:7168
	global_load_lds_dwordx4 v[52:53], off
	v_lshl_add_u64 v[52:53], v[2:3], 0, s[0:1]
	s_add_i32 s1, s28, 0xe000
	s_mov_b32 m0, s1
	s_nop 0
	global_load_lds_dwordx4 v[52:53], off
	s_waitcnt lgkmcnt(8)
	s_barrier
	s_waitcnt lgkmcnt(0)
	s_setprio 1
	s_waitcnt lgkmcnt(0)
	v_mfma_f32_16x16x32_bf16 v[52:55], v[4:7], v[20:23], 0
	v_mfma_f32_16x16x32_bf16 v[56:59], v[12:15], v[20:23], 0
	v_mfma_f32_16x16x32_bf16 v[60:63], v[4:7], v[28:31], 0
	v_mfma_f32_16x16x32_bf16 v[64:67], v[12:15], v[28:31], 0
	v_mfma_f32_16x16x32_bf16 v[68:71], v[4:7], v[36:39], 0
	v_mfma_f32_16x16x32_bf16 v[72:75], v[12:15], v[36:39], 0
	v_mfma_f32_16x16x32_bf16 v[76:79], v[4:7], v[44:47], 0
	v_mfma_f32_16x16x32_bf16 v[80:83], v[12:15], v[44:47], 0
	v_mfma_f32_16x16x32_bf16 v[52:55], v[8:11], v[24:27], v[52:55]
	v_mfma_f32_16x16x32_bf16 v[56:59], v[16:19], v[24:27], v[56:59]
	v_mfma_f32_16x16x32_bf16 v[60:63], v[8:11], v[32:35], v[60:63]
	v_mfma_f32_16x16x32_bf16 v[64:67], v[16:19], v[32:35], v[64:67]
	v_mfma_f32_16x16x32_bf16 v[68:71], v[8:11], v[40:43], v[68:71]
	v_mfma_f32_16x16x32_bf16 v[72:75], v[16:19], v[40:43], v[72:75]
	v_mfma_f32_16x16x32_bf16 v[76:79], v[8:11], v[48:51], v[76:79]
	v_mfma_f32_16x16x32_bf16 v[80:83], v[16:19], v[48:51], v[80:83]
	s_setprio 0
	s_barrier
	v_lshl_add_u64 v[136:137], s[12:13], 0, v[142:143]
	s_add_i32 s13, s95, s27
	v_lshl_add_u64 v[100:101], v[136:137], 0, s[62:63]
	s_mov_b32 m0, s13
	s_mov_b64 s[30:31], 0x20100
	s_add_i32 s12, s13, 0x2000
	ds_read_b128 v[84:87], v160
	ds_read_b128 v[88:91], v160 offset:1024
	ds_read_b128 v[92:95], v160 offset:2048
	ds_read_b128 v[96:99], v160 offset:3072
	global_load_lds_dwordx4 v[100:101], off
	v_lshl_add_u64 v[100:101], v[136:137], 0, s[30:31]
	s_mov_b32 m0, s12
	s_nop 0
	global_load_lds_dwordx4 v[100:101], off
	s_barrier
	s_waitcnt lgkmcnt(0)
	s_setprio 1
	s_waitcnt lgkmcnt(0)
	v_mfma_f32_16x16x32_bf16 v[100:103], v[84:87], v[20:23], 0
	v_mfma_f32_16x16x32_bf16 v[20:23], v[92:95], v[20:23], 0
	v_mfma_f32_16x16x32_bf16 v[100:103], v[88:91], v[24:27], v[100:103]
	v_mfma_f32_16x16x32_bf16 v[20:23], v[96:99], v[24:27], v[20:23]
	v_mfma_f32_16x16x32_bf16 v[24:27], v[84:87], v[28:31], 0
	v_mfma_f32_16x16x32_bf16 v[28:31], v[92:95], v[28:31], 0
	v_mfma_f32_16x16x32_bf16 v[24:27], v[88:91], v[32:35], v[24:27]
	v_mfma_f32_16x16x32_bf16 v[28:31], v[96:99], v[32:35], v[28:31]
	v_mfma_f32_16x16x32_bf16 v[32:35], v[84:87], v[36:39], 0
	v_mfma_f32_16x16x32_bf16 v[36:39], v[92:95], v[36:39], 0
	v_mfma_f32_16x16x32_bf16 v[32:35], v[88:91], v[40:43], v[32:35]
	v_mfma_f32_16x16x32_bf16 v[36:39], v[96:99], v[40:43], v[36:39]
	v_mfma_f32_16x16x32_bf16 v[40:43], v[84:87], v[44:47], 0
	v_mfma_f32_16x16x32_bf16 v[44:47], v[92:95], v[44:47], 0
	v_mfma_f32_16x16x32_bf16 v[40:43], v[88:91], v[48:51], v[40:43]
	v_mfma_f32_16x16x32_bf16 v[44:47], v[96:99], v[48:51], v[44:47]
	s_setprio 0
	s_mov_b32 m0, s28
	v_lshl_add_u64 v[132:133], v[2:3], 0, s[62:63]
	s_mov_b64 s[30:31], 0x8100
	s_barrier
	ds_read_b128 v[48:51], v159 offset:16384
	ds_read_b128 v[104:107], v159 offset:17408
	ds_read_b128 v[108:111], v159 offset:18432
	ds_read_b128 v[112:115], v159 offset:19456
	ds_read_b128 v[116:119], v159 offset:20480
	ds_read_b128 v[120:123], v159 offset:21504
	ds_read_b128 v[124:127], v159 offset:22528
	ds_read_b128 v[128:131], v159 offset:23552
	global_load_lds_dwordx4 v[132:133], off
	v_lshl_add_u64 v[132:133], v[2:3], 0, s[30:31]
	s_mov_b32 m0, s29
	s_nop 0
	global_load_lds_dwordx4 v[132:133], off
	s_barrier
	s_waitcnt lgkmcnt(0)
	s_setprio 1
	s_waitcnt lgkmcnt(0)
	v_mfma_f32_16x16x32_bf16 v[132:135], v[4:7], v[48:51], 0
	v_mfma_f32_16x16x32_bf16 v[148:151], v[4:7], v[108:111], 0
	v_mfma_f32_16x16x32_bf16 v[162:165], v[4:7], v[116:119], 0
	v_mfma_f32_16x16x32_bf16 v[4:7], v[4:7], v[124:127], 0
	v_mfma_f32_16x16x32_bf16 v[132:135], v[8:11], v[104:107], v[132:135]
	v_mfma_f32_16x16x32_bf16 v[148:151], v[8:11], v[112:115], v[148:151]
	v_mfma_f32_16x16x32_bf16 v[162:165], v[8:11], v[120:123], v[162:165]
	v_mfma_f32_16x16x32_bf16 v[4:7], v[8:11], v[128:131], v[4:7]
	v_mfma_f32_16x16x32_bf16 v[8:11], v[12:15], v[124:127], 0
	v_mfma_f32_16x16x32_bf16 v[144:147], v[12:15], v[48:51], 0
	v_mfma_f32_16x16x32_bf16 v[152:155], v[12:15], v[108:111], 0
	v_mfma_f32_16x16x32_bf16 v[166:169], v[12:15], v[116:119], 0
	v_mfma_f32_16x16x32_bf16 v[8:11], v[16:19], v[128:131], v[8:11]
	v_mfma_f32_16x16x32_bf16 v[144:147], v[16:19], v[104:107], v[144:147]
	v_mfma_f32_16x16x32_bf16 v[152:155], v[16:19], v[112:115], v[152:155]
	v_mfma_f32_16x16x32_bf16 v[166:169], v[16:19], v[120:123], v[166:169]
	s_setprio 0
	s_barrier
	s_mov_b64 s[30:31], 0x40100
	s_add_i32 s36, s96, s27
	v_lshl_add_u64 v[12:13], v[136:137], 0, s[30:31]
	s_mov_b32 m0, s36
	s_mov_b64 s[30:31], 0x60100
	s_add_i32 s75, s36, 0x2000
	global_load_lds_dwordx4 v[12:13], off
	v_lshl_add_u64 v[12:13], v[136:137], 0, s[30:31]
	s_mov_b32 m0, s75
	s_nop 0
	global_load_lds_dwordx4 v[12:13], off
	s_waitcnt vmcnt(6)
	s_barrier
	s_setprio 1
	v_mfma_f32_16x16x32_bf16 v[12:15], v[84:87], v[48:51], 0
	v_mfma_f32_16x16x32_bf16 v[16:19], v[92:95], v[48:51], 0
	v_mfma_f32_16x16x32_bf16 v[12:15], v[88:91], v[104:107], v[12:15]
	v_mfma_f32_16x16x32_bf16 v[16:19], v[96:99], v[104:107], v[16:19]
	v_mfma_f32_16x16x32_bf16 v[48:51], v[84:87], v[108:111], 0
	v_mfma_f32_16x16x32_bf16 v[104:107], v[92:95], v[108:111], 0
	v_mfma_f32_16x16x32_bf16 v[108:111], v[84:87], v[116:119], 0
	v_mfma_f32_16x16x32_bf16 v[84:87], v[84:87], v[124:127], 0
	v_mfma_f32_16x16x32_bf16 v[48:51], v[88:91], v[112:115], v[48:51]
	v_mfma_f32_16x16x32_bf16 v[104:107], v[96:99], v[112:115], v[104:107]
	v_mfma_f32_16x16x32_bf16 v[108:111], v[88:91], v[120:123], v[108:111]
	v_mfma_f32_16x16x32_bf16 v[112:115], v[92:95], v[116:119], 0
	v_mfma_f32_16x16x32_bf16 v[84:87], v[88:91], v[128:131], v[84:87]
	v_mfma_f32_16x16x32_bf16 v[88:91], v[92:95], v[124:127], 0
	v_mfma_f32_16x16x32_bf16 v[112:115], v[96:99], v[120:123], v[112:115]
	v_mfma_f32_16x16x32_bf16 v[88:91], v[96:99], v[128:131], v[88:91]
	s_setprio 0
	s_add_i32 s81, 0, 0x18000
	v_add_u32_e32 v161, s81, v157
	s_barrier
	ds_read_b128 v[92:95], v161
	ds_read_b128 v[96:99], v161 offset:1024
	ds_read_b128 v[116:119], v161 offset:2048
	ds_read_b128 v[120:123], v161 offset:3072
	s_mov_b64 s[30:31], 0x10100
	s_mov_b32 m0, s33
	v_lshl_add_u64 v[194:195], v[2:3], 0, s[30:31]
	s_mov_b64 s[30:31], 0x18100
	ds_read_b128 v[124:127], v159 offset:32768
	ds_read_b128 v[128:131], v159 offset:33792
	ds_read_b128 v[170:173], v159 offset:34816
	ds_read_b128 v[174:177], v159 offset:35840
	ds_read_b128 v[178:181], v159 offset:36864
	ds_read_b128 v[182:185], v159 offset:37888
	ds_read_b128 v[186:189], v159 offset:38912
	ds_read_b128 v[190:193], v159 offset:39936
	global_load_lds_dwordx4 v[194:195], off
	v_lshl_add_u64 v[194:195], v[2:3], 0, s[30:31]
	s_mov_b32 m0, s39
	s_nop 0
	global_load_lds_dwordx4 v[194:195], off
	s_waitcnt lgkmcnt(8)
	s_barrier
	s_waitcnt lgkmcnt(0)
	s_setprio 1
	s_waitcnt lgkmcnt(0)
	v_mfma_f32_16x16x32_bf16 v[52:55], v[92:95], v[124:127], v[52:55]
	v_mfma_f32_16x16x32_bf16 v[56:59], v[116:119], v[124:127], v[56:59]
	v_mfma_f32_16x16x32_bf16 v[60:63], v[92:95], v[170:173], v[60:63]
	v_mfma_f32_16x16x32_bf16 v[64:67], v[116:119], v[170:173], v[64:67]
	v_mfma_f32_16x16x32_bf16 v[68:71], v[92:95], v[178:181], v[68:71]
	v_mfma_f32_16x16x32_bf16 v[72:75], v[116:119], v[178:181], v[72:75]
	v_mfma_f32_16x16x32_bf16 v[76:79], v[92:95], v[186:189], v[76:79]
	v_mfma_f32_16x16x32_bf16 v[80:83], v[116:119], v[186:189], v[80:83]
	v_mfma_f32_16x16x32_bf16 v[52:55], v[96:99], v[128:131], v[52:55]
	v_mfma_f32_16x16x32_bf16 v[56:59], v[120:123], v[128:131], v[56:59]
	v_mfma_f32_16x16x32_bf16 v[60:63], v[96:99], v[174:177], v[60:63]
	v_mfma_f32_16x16x32_bf16 v[64:67], v[120:123], v[174:177], v[64:67]
	v_mfma_f32_16x16x32_bf16 v[68:71], v[96:99], v[182:185], v[68:71]
	v_mfma_f32_16x16x32_bf16 v[72:75], v[120:123], v[182:185], v[72:75]
	v_mfma_f32_16x16x32_bf16 v[76:79], v[96:99], v[190:193], v[76:79]
	v_mfma_f32_16x16x32_bf16 v[80:83], v[120:123], v[190:193], v[80:83]
	s_setprio 0
	s_barrier
	s_add_i32 s97, 0, 0x1c000
	s_add_i32 s81, s81, s27
	v_add_u32_e32 v242, s97, v157
	v_lshl_add_u64 v[210:211], v[136:137], 0, s[64:65]
	s_mov_b32 m0, s81
	s_mov_b64 s[30:31], 0x20180
	s_add_i32 s80, s81, 0x2000
	ds_read_b128 v[194:197], v242
	ds_read_b128 v[198:201], v242 offset:1024
	ds_read_b128 v[202:205], v242 offset:2048
	ds_read_b128 v[206:209], v242 offset:3072
	global_load_lds_dwordx4 v[210:211], off
	v_lshl_add_u64 v[210:211], v[136:137], 0, s[30:31]
	s_mov_b32 m0, s80
	s_nop 0
	global_load_lds_dwordx4 v[210:211], off
	s_barrier
	s_waitcnt lgkmcnt(0)
	s_setprio 1
	s_waitcnt lgkmcnt(0)
	v_mfma_f32_16x16x32_bf16 v[100:103], v[194:197], v[124:127], v[100:103]
	v_mfma_f32_16x16x32_bf16 v[20:23], v[202:205], v[124:127], v[20:23]
	v_mfma_f32_16x16x32_bf16 v[24:27], v[194:197], v[170:173], v[24:27]
	v_mfma_f32_16x16x32_bf16 v[28:31], v[202:205], v[170:173], v[28:31]
	v_mfma_f32_16x16x32_bf16 v[32:35], v[194:197], v[178:181], v[32:35]
	v_mfma_f32_16x16x32_bf16 v[36:39], v[202:205], v[178:181], v[36:39]
	v_mfma_f32_16x16x32_bf16 v[40:43], v[194:197], v[186:189], v[40:43]
	v_mfma_f32_16x16x32_bf16 v[44:47], v[202:205], v[186:189], v[44:47]
	v_mfma_f32_16x16x32_bf16 v[100:103], v[198:201], v[128:131], v[100:103]
	v_mfma_f32_16x16x32_bf16 v[20:23], v[206:209], v[128:131], v[20:23]
	v_mfma_f32_16x16x32_bf16 v[24:27], v[198:201], v[174:177], v[24:27]
	v_mfma_f32_16x16x32_bf16 v[28:31], v[206:209], v[174:177], v[28:31]
	v_mfma_f32_16x16x32_bf16 v[32:35], v[198:201], v[182:185], v[32:35]
	v_mfma_f32_16x16x32_bf16 v[36:39], v[206:209], v[182:185], v[36:39]
	v_mfma_f32_16x16x32_bf16 v[40:43], v[198:201], v[190:193], v[40:43]
	v_mfma_f32_16x16x32_bf16 v[44:47], v[206:209], v[190:193], v[44:47]
	s_setprio 0
	s_mov_b32 m0, s90
	v_lshl_add_u64 v[210:211], v[2:3], 0, s[64:65]
	s_mov_b64 s[30:31], 0x8180
	s_barrier
	ds_read_b128 v[124:127], v159 offset:49152
	ds_read_b128 v[128:131], v159 offset:50176
	ds_read_b128 v[170:173], v159 offset:51200
	ds_read_b128 v[174:177], v159 offset:52224
	ds_read_b128 v[178:181], v159 offset:53248
	ds_read_b128 v[182:185], v159 offset:54272
	ds_read_b128 v[186:189], v159 offset:55296
	ds_read_b128 v[190:193], v159 offset:56320
	global_load_lds_dwordx4 v[210:211], off
	v_lshl_add_u64 v[210:211], v[2:3], 0, s[30:31]
	s_mov_b32 m0, s91
	s_nop 0
	global_load_lds_dwordx4 v[210:211], off
	s_barrier
	s_waitcnt lgkmcnt(0)
	s_setprio 1
	s_waitcnt lgkmcnt(0)
	v_mfma_f32_16x16x32_bf16 v[4:7], v[92:95], v[186:189], v[4:7]
	v_mfma_f32_16x16x32_bf16 v[8:11], v[116:119], v[186:189], v[8:11]
	v_mfma_f32_16x16x32_bf16 v[132:135], v[92:95], v[124:127], v[132:135]
	v_mfma_f32_16x16x32_bf16 v[144:147], v[116:119], v[124:127], v[144:147]
	v_mfma_f32_16x16x32_bf16 v[148:151], v[92:95], v[170:173], v[148:151]
	v_mfma_f32_16x16x32_bf16 v[152:155], v[116:119], v[170:173], v[152:155]
	v_mfma_f32_16x16x32_bf16 v[162:165], v[92:95], v[178:181], v[162:165]
	v_mfma_f32_16x16x32_bf16 v[166:169], v[116:119], v[178:181], v[166:169]
	v_mfma_f32_16x16x32_bf16 v[4:7], v[96:99], v[190:193], v[4:7]
	v_mfma_f32_16x16x32_bf16 v[8:11], v[120:123], v[190:193], v[8:11]
	v_mfma_f32_16x16x32_bf16 v[132:135], v[96:99], v[128:131], v[132:135]
	v_mfma_f32_16x16x32_bf16 v[144:147], v[120:123], v[128:131], v[144:147]
	v_mfma_f32_16x16x32_bf16 v[148:151], v[96:99], v[174:177], v[148:151]
	v_mfma_f32_16x16x32_bf16 v[152:155], v[120:123], v[174:177], v[152:155]
	v_mfma_f32_16x16x32_bf16 v[162:165], v[96:99], v[182:185], v[162:165]
	v_mfma_f32_16x16x32_bf16 v[166:169], v[120:123], v[182:185], v[166:169]
	s_setprio 0
	s_barrier
	s_mov_b64 s[30:31], 0x40180
	s_add_i32 s97, s97, s27
	v_lshl_add_u64 v[92:93], v[136:137], 0, s[30:31]
	s_mov_b32 m0, s97
	s_mov_b64 s[30:31], 0x60180
	s_add_i32 vcc_lo, s97, 0x2000
	global_load_lds_dwordx4 v[92:93], off
	v_lshl_add_u64 v[92:93], v[136:137], 0, s[30:31]
	s_mov_b32 m0, vcc_lo
	s_nop 0
	global_load_lds_dwordx4 v[92:93], off
	s_waitcnt vmcnt(6)
	s_barrier
	s_setprio 1
	v_mfma_f32_16x16x32_bf16 v[12:15], v[194:197], v[124:127], v[12:15]
	v_mfma_f32_16x16x32_bf16 v[16:19], v[202:205], v[124:127], v[16:19]
	v_mfma_f32_16x16x32_bf16 v[48:51], v[194:197], v[170:173], v[48:51]
	v_mfma_f32_16x16x32_bf16 v[92:95], v[202:205], v[170:173], v[104:107]
	v_mfma_f32_16x16x32_bf16 v[96:99], v[194:197], v[178:181], v[108:111]
	v_mfma_f32_16x16x32_bf16 v[104:107], v[202:205], v[178:181], v[112:115]
	v_mfma_f32_16x16x32_bf16 v[84:87], v[194:197], v[186:189], v[84:87]
	v_mfma_f32_16x16x32_bf16 v[88:91], v[202:205], v[186:189], v[88:91]
	v_mfma_f32_16x16x32_bf16 v[12:15], v[198:201], v[128:131], v[12:15]
	v_mfma_f32_16x16x32_bf16 v[16:19], v[206:209], v[128:131], v[16:19]
	v_mfma_f32_16x16x32_bf16 v[48:51], v[198:201], v[174:177], v[48:51]
	v_mfma_f32_16x16x32_bf16 v[92:95], v[206:209], v[174:177], v[92:95]
	v_mfma_f32_16x16x32_bf16 v[96:99], v[198:201], v[182:185], v[96:99]
	v_mfma_f32_16x16x32_bf16 v[104:107], v[206:209], v[182:185], v[104:107]
	v_mfma_f32_16x16x32_bf16 v[84:87], v[198:201], v[190:193], v[84:87]
	v_mfma_f32_16x16x32_bf16 v[88:91], v[206:209], v[190:193], v[88:91]
	s_setprio 0
	s_barrier
	ds_read_b128 v[108:111], v158
	ds_read_b128 v[112:115], v158 offset:1024
	ds_read_b128 v[116:119], v158 offset:2048
	ds_read_b128 v[120:123], v158 offset:3072
	s_mov_b64 s[30:31], 0x10180
	s_mov_b32 m0, s77
	v_lshl_add_u64 v[136:137], v[2:3], 0, s[30:31]
	s_mov_b64 s[30:31], 0x18180
	ds_read_b128 v[124:127], v159
	ds_read_b128 v[128:131], v159 offset:1024
	ds_read_b128 v[170:173], v159 offset:2048
	ds_read_b128 v[174:177], v159 offset:3072
	ds_read_b128 v[178:181], v159 offset:4096
	ds_read_b128 v[182:185], v159 offset:5120
	ds_read_b128 v[186:189], v159 offset:6144
	ds_read_b128 v[190:193], v159 offset:7168
	global_load_lds_dwordx4 v[136:137], off
	v_lshl_add_u64 v[2:3], v[2:3], 0, s[30:31]
	s_mov_b32 m0, s1
	s_nop 0
	global_load_lds_dwordx4 v[2:3], off
	s_waitcnt lgkmcnt(8)
	s_barrier
	s_waitcnt lgkmcnt(0)
	s_setprio 1
	s_waitcnt lgkmcnt(0)
	v_mfma_f32_16x16x32_bf16 v[52:55], v[108:111], v[124:127], v[52:55]
	v_mfma_f32_16x16x32_bf16 v[56:59], v[116:119], v[124:127], v[56:59]
	v_mfma_f32_16x16x32_bf16 v[60:63], v[108:111], v[170:173], v[60:63]
	v_mfma_f32_16x16x32_bf16 v[64:67], v[116:119], v[170:173], v[64:67]
	v_mfma_f32_16x16x32_bf16 v[68:71], v[108:111], v[178:181], v[68:71]
	v_mfma_f32_16x16x32_bf16 v[72:75], v[116:119], v[178:181], v[72:75]
	v_mfma_f32_16x16x32_bf16 v[76:79], v[108:111], v[186:189], v[76:79]
	v_mfma_f32_16x16x32_bf16 v[80:83], v[116:119], v[186:189], v[80:83]
	v_mfma_f32_16x16x32_bf16 v[52:55], v[112:115], v[128:131], v[52:55]
	v_mfma_f32_16x16x32_bf16 v[56:59], v[120:123], v[128:131], v[56:59]
	v_mfma_f32_16x16x32_bf16 v[60:63], v[112:115], v[174:177], v[60:63]
	v_mfma_f32_16x16x32_bf16 v[64:67], v[120:123], v[174:177], v[64:67]
	v_mfma_f32_16x16x32_bf16 v[68:71], v[112:115], v[182:185], v[68:71]
	v_mfma_f32_16x16x32_bf16 v[72:75], v[120:123], v[182:185], v[72:75]
	v_mfma_f32_16x16x32_bf16 v[76:79], v[112:115], v[190:193], v[76:79]
	v_mfma_f32_16x16x32_bf16 v[80:83], v[120:123], v[190:193], v[80:83]
	s_setprio 0
	s_barrier
	s_mov_b32 m0, s13
	v_lshl_add_u64 v[136:137], s[82:83], 0, v[142:143]
	ds_read_b128 v[194:197], v160
	ds_read_b128 v[198:201], v160 offset:1024
	ds_read_b128 v[202:205], v160 offset:2048
	ds_read_b128 v[206:209], v160 offset:3072
	global_load_lds_dwordx4 v[136:137], off
	v_lshl_add_u64 v[2:3], v[136:137], 0, s[14:15]
	s_mov_b32 m0, s12
	s_nop 0
	global_load_lds_dwordx4 v[2:3], off
	s_barrier
	s_waitcnt lgkmcnt(0)
	s_setprio 1
	s_waitcnt lgkmcnt(0)
	v_mfma_f32_16x16x32_bf16 v[20:23], v[202:205], v[124:127], v[20:23]
	v_mfma_f32_16x16x32_bf16 v[24:27], v[194:197], v[170:173], v[24:27]
	v_mfma_f32_16x16x32_bf16 v[28:31], v[202:205], v[170:173], v[28:31]
	v_mfma_f32_16x16x32_bf16 v[32:35], v[194:197], v[178:181], v[32:35]
	v_mfma_f32_16x16x32_bf16 v[36:39], v[202:205], v[178:181], v[36:39]
	v_mfma_f32_16x16x32_bf16 v[40:43], v[194:197], v[186:189], v[40:43]
	v_mfma_f32_16x16x32_bf16 v[100:103], v[194:197], v[124:127], v[100:103]
	v_mfma_f32_16x16x32_bf16 v[20:23], v[206:209], v[128:131], v[20:23]
	v_mfma_f32_16x16x32_bf16 v[24:27], v[198:201], v[174:177], v[24:27]
	v_mfma_f32_16x16x32_bf16 v[28:31], v[206:209], v[174:177], v[28:31]
	v_mfma_f32_16x16x32_bf16 v[32:35], v[198:201], v[182:185], v[32:35]
	v_mfma_f32_16x16x32_bf16 v[36:39], v[206:209], v[182:185], v[36:39]
	v_mfma_f32_16x16x32_bf16 v[170:173], v[198:201], v[190:193], v[40:43]
	v_mfma_f32_16x16x32_bf16 v[40:43], v[202:205], v[186:189], v[44:47]
	v_mfma_f32_16x16x32_bf16 v[210:213], v[198:201], v[128:131], v[100:103]
	v_mfma_f32_16x16x32_bf16 v[174:177], v[206:209], v[190:193], v[40:43]
	s_setprio 0
	s_mov_b32 m0, s28
	v_lshl_add_u64 v[250:251], s[78:79], 0, v[140:141]
	s_barrier
	s_nop 1
	ds_read_b128 v[40:43], v159 offset:16384
	ds_read_b128 v[44:47], v159 offset:17408
	ds_read_b128 v[100:103], v159 offset:18432
	ds_read_b128 v[124:127], v159 offset:19456
	ds_read_b128 v[128:131], v159 offset:20480
	ds_read_b128 v[178:181], v159 offset:21504
	ds_read_b128 v[182:185], v159 offset:22528
	ds_read_b128 v[186:189], v159 offset:23552
	global_load_lds_dwordx4 v[250:251], off
	v_lshl_add_u64 v[2:3], v[250:251], 0, s[20:21]
	s_mov_b32 m0, s29
	s_nop 0
	global_load_lds_dwordx4 v[2:3], off
	s_barrier
	s_waitcnt lgkmcnt(0)
	s_setprio 1
	s_waitcnt lgkmcnt(0)
	v_mfma_f32_16x16x32_bf16 v[2:5], v[108:111], v[182:185], v[4:7]
	v_mfma_f32_16x16x32_bf16 v[6:9], v[116:119], v[182:185], v[8:11]
	v_mfma_f32_16x16x32_bf16 v[132:135], v[108:111], v[40:43], v[132:135]
	v_mfma_f32_16x16x32_bf16 v[144:147], v[116:119], v[40:43], v[144:147]
	v_mfma_f32_16x16x32_bf16 v[148:151], v[108:111], v[100:103], v[148:151]
	v_mfma_f32_16x16x32_bf16 v[152:155], v[116:119], v[100:103], v[152:155]
	v_mfma_f32_16x16x32_bf16 v[162:165], v[108:111], v[128:131], v[162:165]
	v_mfma_f32_16x16x32_bf16 v[166:169], v[116:119], v[128:131], v[166:169]
	v_mfma_f32_16x16x32_bf16 v[2:5], v[112:115], v[186:189], v[2:5]
	v_mfma_f32_16x16x32_bf16 v[6:9], v[120:123], v[186:189], v[6:9]
	v_mfma_f32_16x16x32_bf16 v[132:135], v[112:115], v[44:47], v[132:135]
	v_mfma_f32_16x16x32_bf16 v[144:147], v[120:123], v[44:47], v[144:147]
	v_mfma_f32_16x16x32_bf16 v[148:151], v[112:115], v[124:127], v[148:151]
	v_mfma_f32_16x16x32_bf16 v[152:155], v[120:123], v[124:127], v[152:155]
	v_mfma_f32_16x16x32_bf16 v[162:165], v[112:115], v[178:181], v[162:165]
	v_mfma_f32_16x16x32_bf16 v[166:169], v[120:123], v[178:181], v[166:169]
	s_setprio 0
	s_barrier
	s_mov_b32 m0, s36
	v_lshl_add_u64 v[10:11], v[136:137], 0, s[22:23]
	global_load_lds_dwordx4 v[10:11], off
	v_lshl_add_u64 v[10:11], v[136:137], 0, s[42:43]
	s_mov_b32 m0, s75
	s_nop 0
	global_load_lds_dwordx4 v[10:11], off
	s_waitcnt vmcnt(6)
	s_barrier
	s_setprio 1
	v_mfma_f32_16x16x32_bf16 v[10:13], v[194:197], v[40:43], v[12:15]
	v_mfma_f32_16x16x32_bf16 v[14:17], v[202:205], v[40:43], v[16:19]
	v_mfma_f32_16x16x32_bf16 v[40:43], v[194:197], v[100:103], v[48:51]
	v_mfma_f32_16x16x32_bf16 v[190:193], v[198:201], v[124:127], v[40:43]
	v_mfma_f32_16x16x32_bf16 v[40:43], v[202:205], v[100:103], v[92:95]
	v_mfma_f32_16x16x32_bf16 v[214:217], v[206:209], v[124:127], v[40:43]
	v_mfma_f32_16x16x32_bf16 v[40:43], v[194:197], v[128:131], v[96:99]
	v_mfma_f32_16x16x32_bf16 v[218:221], v[198:201], v[178:181], v[40:43]
	v_mfma_f32_16x16x32_bf16 v[40:43], v[202:205], v[128:131], v[104:107]
	v_mfma_f32_16x16x32_bf16 v[178:181], v[206:209], v[178:181], v[40:43]
	v_mfma_f32_16x16x32_bf16 v[40:43], v[194:197], v[182:185], v[84:87]
	v_mfma_f32_16x16x32_bf16 v[10:13], v[198:201], v[44:47], v[10:13]
	v_mfma_f32_16x16x32_bf16 v[14:17], v[206:209], v[44:47], v[14:17]
	v_mfma_f32_16x16x32_bf16 v[194:197], v[198:201], v[186:189], v[40:43]
	v_mfma_f32_16x16x32_bf16 v[40:43], v[202:205], v[182:185], v[88:91]
	v_mfma_f32_16x16x32_bf16 v[182:185], v[206:209], v[186:189], v[40:43]
	s_setprio 0
	s_barrier
	ds_read_b128 v[186:189], v161
	ds_read_b128 v[198:201], v161 offset:1024
	ds_read_b128 v[202:205], v161 offset:2048
	ds_read_b128 v[206:209], v161 offset:3072
	s_mov_b32 m0, s33
	v_lshl_add_u64 v[18:19], v[250:251], 0, s[44:45]
	ds_read_b128 v[40:43], v159 offset:32768
	ds_read_b128 v[44:47], v159 offset:33792
	ds_read_b128 v[48:51], v159 offset:34816
	ds_read_b128 v[84:87], v159 offset:35840
	ds_read_b128 v[88:91], v159 offset:36864
	ds_read_b128 v[92:95], v159 offset:37888
	ds_read_b128 v[222:225], v159 offset:38912
	ds_read_b128 v[226:229], v159 offset:39936
	global_load_lds_dwordx4 v[18:19], off
	v_lshl_add_u64 v[18:19], v[250:251], 0, s[46:47]
	s_mov_b32 m0, s39
	s_nop 0
	global_load_lds_dwordx4 v[18:19], off
	s_waitcnt lgkmcnt(8)
	s_barrier
	s_waitcnt lgkmcnt(0)
	s_setprio 1
	s_waitcnt lgkmcnt(0)
	v_mfma_f32_16x16x32_bf16 v[52:55], v[186:189], v[40:43], v[52:55]
	v_mfma_f32_16x16x32_bf16 v[126:129], v[198:201], v[44:47], v[52:55]
	v_mfma_f32_16x16x32_bf16 v[52:55], v[202:205], v[40:43], v[56:59]
	v_mfma_f32_16x16x32_bf16 v[122:125], v[206:209], v[44:47], v[52:55]
	v_mfma_f32_16x16x32_bf16 v[52:55], v[186:189], v[48:51], v[60:63]
	v_mfma_f32_16x16x32_bf16 v[118:121], v[198:201], v[84:87], v[52:55]
	v_mfma_f32_16x16x32_bf16 v[52:55], v[202:205], v[48:51], v[64:67]
	v_mfma_f32_16x16x32_bf16 v[114:117], v[206:209], v[84:87], v[52:55]
	v_mfma_f32_16x16x32_bf16 v[52:55], v[186:189], v[88:91], v[68:71]
	v_mfma_f32_16x16x32_bf16 v[110:113], v[198:201], v[92:95], v[52:55]
	v_mfma_f32_16x16x32_bf16 v[52:55], v[202:205], v[88:91], v[72:75]
	v_mfma_f32_16x16x32_bf16 v[106:109], v[206:209], v[92:95], v[52:55]
	v_mfma_f32_16x16x32_bf16 v[52:55], v[186:189], v[222:225], v[76:79]
	v_mfma_f32_16x16x32_bf16 v[102:105], v[198:201], v[226:229], v[52:55]
	v_mfma_f32_16x16x32_bf16 v[52:55], v[202:205], v[222:225], v[80:83]
	v_mfma_f32_16x16x32_bf16 v[98:101], v[206:209], v[226:229], v[52:55]
	s_setprio 0
	s_barrier
	s_mov_b32 m0, s81
	v_lshl_add_u64 v[18:19], v[136:137], 0, s[18:19]
	ds_read_b128 v[230:233], v242
	ds_read_b128 v[234:237], v242 offset:1024
	ds_read_b128 v[238:241], v242 offset:2048
	ds_read_b128 v[242:245], v242 offset:3072
	global_load_lds_dwordx4 v[18:19], off
	v_lshl_add_u64 v[18:19], v[136:137], 0, s[52:53]
	s_mov_b32 m0, s80
	s_nop 0
	global_load_lds_dwordx4 v[18:19], off
	s_barrier
	s_waitcnt lgkmcnt(0)
	s_setprio 1
	s_waitcnt lgkmcnt(0)
	v_mfma_f32_16x16x32_bf16 v[18:21], v[238:241], v[40:43], v[20:23]
	v_mfma_f32_16x16x32_bf16 v[52:55], v[230:233], v[40:43], v[210:213]
	v_mfma_f32_16x16x32_bf16 v[58:61], v[242:245], v[44:47], v[18:21]
	v_mfma_f32_16x16x32_bf16 v[18:21], v[230:233], v[48:51], v[24:27]
	v_mfma_f32_16x16x32_bf16 v[62:65], v[234:237], v[44:47], v[52:55]
	v_mfma_f32_16x16x32_bf16 v[54:57], v[234:237], v[84:87], v[18:21]
	v_mfma_f32_16x16x32_bf16 v[18:21], v[238:241], v[48:51], v[28:31]
	v_mfma_f32_16x16x32_bf16 v[50:53], v[242:245], v[84:87], v[18:21]
	v_mfma_f32_16x16x32_bf16 v[18:21], v[230:233], v[88:91], v[32:35]
	v_mfma_f32_16x16x32_bf16 v[46:49], v[234:237], v[92:95], v[18:21]
	v_mfma_f32_16x16x32_bf16 v[18:21], v[238:241], v[88:91], v[36:39]
	v_mfma_f32_16x16x32_bf16 v[42:45], v[242:245], v[92:95], v[18:21]
	v_mfma_f32_16x16x32_bf16 v[18:21], v[230:233], v[222:225], v[170:173]
	v_mfma_f32_16x16x32_bf16 v[38:41], v[234:237], v[226:229], v[18:21]
	v_mfma_f32_16x16x32_bf16 v[18:21], v[238:241], v[222:225], v[174:177]
	v_mfma_f32_16x16x32_bf16 v[34:37], v[242:245], v[226:229], v[18:21]
	s_setprio 0
	s_mov_b32 m0, s90
	v_lshl_add_u64 v[26:27], v[250:251], 0, s[18:19]
	s_barrier
	s_nop 2
	ds_read_b128 v[18:21], v159 offset:49152
	ds_read_b128 v[22:25], v159 offset:50176
	ds_read_b128 v[170:173], v159 offset:51200
	ds_read_b128 v[174:177], v159 offset:52224
	ds_read_b128 v[210:213], v159 offset:53248
	ds_read_b128 v[222:225], v159 offset:54272
	ds_read_b128 v[226:229], v159 offset:55296
	ds_read_b128 v[246:249], v159 offset:56320
	global_load_lds_dwordx4 v[26:27], off
	v_lshl_add_u64 v[26:27], v[250:251], 0, s[54:55]
	s_mov_b32 m0, s91
	s_nop 0
	global_load_lds_dwordx4 v[26:27], off
	s_barrier
	s_waitcnt lgkmcnt(0)
	s_setprio 1
	s_waitcnt lgkmcnt(0)
	v_mfma_f32_16x16x32_bf16 v[26:29], v[186:189], v[18:21], v[132:135]
	v_mfma_f32_16x16x32_bf16 v[94:97], v[198:201], v[22:25], v[26:29]
	v_mfma_f32_16x16x32_bf16 v[26:29], v[202:205], v[18:21], v[144:147]
	v_mfma_f32_16x16x32_bf16 v[90:93], v[206:209], v[22:25], v[26:29]
	v_mfma_f32_16x16x32_bf16 v[26:29], v[186:189], v[170:173], v[148:151]
	v_mfma_f32_16x16x32_bf16 v[86:89], v[198:201], v[174:177], v[26:29]
	v_mfma_f32_16x16x32_bf16 v[26:29], v[202:205], v[170:173], v[152:155]
	v_mfma_f32_16x16x32_bf16 v[82:85], v[206:209], v[174:177], v[26:29]
	v_mfma_f32_16x16x32_bf16 v[26:29], v[186:189], v[210:213], v[162:165]
	v_mfma_f32_16x16x32_bf16 v[2:5], v[186:189], v[226:229], v[2:5]
	v_mfma_f32_16x16x32_bf16 v[78:81], v[198:201], v[222:225], v[26:29]
	v_mfma_f32_16x16x32_bf16 v[26:29], v[202:205], v[210:213], v[166:169]
	v_mfma_f32_16x16x32_bf16 v[70:73], v[198:201], v[246:249], v[2:5]
	v_mfma_f32_16x16x32_bf16 v[2:5], v[202:205], v[226:229], v[6:9]
	v_mfma_f32_16x16x32_bf16 v[74:77], v[206:209], v[222:225], v[26:29]
	v_mfma_f32_16x16x32_bf16 v[66:69], v[206:209], v[246:249], v[2:5]
	s_setprio 0
	s_barrier
	s_mov_b32 m0, s97
	s_nop 2
	v_lshl_add_u64 v[2:3], v[136:137], 0, s[56:57]
	global_load_lds_dwordx4 v[2:3], off
	v_lshl_add_u64 v[2:3], v[136:137], 0, s[58:59]
	s_mov_b32 m0, vcc_lo
	s_nop 0
	global_load_lds_dwordx4 v[2:3], off
	v_readfirstlane_b32 s98, v0
	s_cmp_lg_u32 s98, 0
	s_cbranch_scc1 .Lp4w_skip
	v_readlane_b32 s100, v254, 13
	v_readlane_b32 s101, v254, 14
	v_mov_b32_e32 v252, 0x22004
	ds_read_b32 v253, v252
	v_mov_b32_e32 v252, 0x2b5d024
	s_mov_b32 s32, 0x100000
	s_waitcnt lgkmcnt(0)
	v_readfirstlane_b32 s98, v253
	s_nop 4
.Lp4w_poll:
	global_load_dword v253, v252, s[100:101] sc1
	s_waitcnt vmcnt(0)
	v_readfirstlane_b32 s99, v253
	s_cmp_ge_u32 s99, s98
	s_cbranch_scc1 .Lp4w_done
	s_sleep 1
	s_sub_u32 s32, s32, 1
	s_cmp_lg_u32 s32, 0
	s_cbranch_scc1 .Lp4w_poll

.Lp4w_skip:
	s_waitcnt vmcnt(6)
	s_barrier
	s_setprio 1
	v_mfma_f32_16x16x32_bf16 v[2:5], v[230:233], v[18:21], v[10:13]
	v_mfma_f32_16x16x32_bf16 v[30:33], v[234:237], v[22:25], v[2:5]
	v_mfma_f32_16x16x32_bf16 v[2:5], v[238:241], v[18:21], v[14:17]
	v_mfma_f32_16x16x32_bf16 v[26:29], v[242:245], v[22:25], v[2:5]
	v_mfma_f32_16x16x32_bf16 v[2:5], v[230:233], v[170:173], v[190:193]
	v_mfma_f32_16x16x32_bf16 v[22:25], v[234:237], v[174:177], v[2:5]
	v_mfma_f32_16x16x32_bf16 v[2:5], v[238:241], v[170:173], v[214:217]
	v_mfma_f32_16x16x32_bf16 v[18:21], v[242:245], v[174:177], v[2:5]
	v_mfma_f32_16x16x32_bf16 v[2:5], v[230:233], v[210:213], v[218:221]
	v_mfma_f32_16x16x32_bf16 v[14:17], v[234:237], v[222:225], v[2:5]
	v_mfma_f32_16x16x32_bf16 v[2:5], v[238:241], v[210:213], v[178:181]
	v_mfma_f32_16x16x32_bf16 v[10:13], v[242:245], v[222:225], v[2:5]
	v_mfma_f32_16x16x32_bf16 v[2:5], v[230:233], v[226:229], v[194:197]
	v_mfma_f32_16x16x32_bf16 v[6:9], v[234:237], v[246:249], v[2:5]
	v_mfma_f32_16x16x32_bf16 v[2:5], v[238:241], v[226:229], v[182:185]
	v_mfma_f32_16x16x32_bf16 v[2:5], v[242:245], v[246:249], v[2:5]
	s_setprio 0
	s_andn2_b64 vcc, exec, s[60:61]
	s_barrier
	s_cbranch_vccnz .LBB0_689
	s_barrier
